# xcd barrier instead of cg grid.sync; WABST rope rows batched loads; MLA prompt loop regenerated: K-frag prefetch, linear stage store/load, 32-bit offset pointer increments
# speedup vs baseline: 1.0192x; 1.0073x over previous
.LBB0_180:
	s_mul_hi_i32 s12, s3, 0xa57eb503
	s_add_i32 s12, s12, s3
	s_lshr_b32 s13, s12, 31
	s_ashr_i32 s14, s12, 7
	s_add_i32 s14, s14, s13
	s_mul_i32 s12, s14, 0xc6
	s_sub_i32 s12, s3, s12
	s_mul_i32 s13, s12, 0x7c2
	s_lshr_b32 s15, s13, 31
	s_lshr_b32 s13, s13, 16
	s_add_i32 s13, s13, s15
	s_sext_i32_i16 s15, s13
	v_lshl_or_b32 v2, s15, 6, v66
	v_ashrrev_i32_e32 v3, 31, v2
	s_waitcnt lgkmcnt(0)
	v_lshl_add_u64 v[4:5], v[2:3], 2, s[4:5]
	global_load_dword v68, v[4:5], off
	s_mul_i32 s13, s13, 33
	s_sub_i32 s15, s12, s13
	v_mul_hi_i32_i24_e32 v5, 0x1800, v2
	v_mul_i32_i24_e32 v4, 0x1800, v2
	s_mul_i32 s12, s14, 0x60
	v_lshl_add_u64 v[4:5], s[6:7], 0, v[4:5]
	s_ashr_i32 s13, s12, 31
	s_sext_i32_i16 s15, s15
	v_lshl_add_u64 v[50:51], s[12:13], 2, v[4:5]
	s_mov_b64 s[12:13], -1
	s_cmp_lt_i32 s15, 32
	s_mul_i32 s20, s14, 0x120
	v_lshl_add_u64 v[70:71], v[2:3], 1, s[10:11]
	s_cbranch_scc1 .LBB0_184
	s_add_i32 s17, s20, 0x100
	global_load_dwordx4 v[14:17], v[50:51], off offset:256
	global_load_dwordx4 v[18:21], v[50:51], off offset:272
	global_load_dwordx4 v[22:25], v[50:51], off offset:288
	global_load_dwordx4 v[26:29], v[50:51], off offset:304
	global_load_dwordx4 v[30:33], v[50:51], off offset:320
	global_load_dwordx4 v[34:37], v[50:51], off offset:336
	global_load_dwordx4 v[38:41], v[50:51], off offset:352
	global_load_dwordx4 v[42:45], v[50:51], off offset:368
	s_waitcnt vmcnt(0)
	v_mov_b32_e32 v69, v68
	s_add_i32 s33, s17, 0
	s_add_i32 s27, s17, 1
	s_add_i32 s42, s17, 2
	s_add_i32 s39, s17, 3
	v_pk_mul_f32 v[2:3], v[68:69], v[14:15]
	v_pk_mul_f32 v[4:5], v[68:69], v[16:17]
	v_mad_i64_i32 v[6:7], s[40:41], s33, v1, v[70:71]
	v_mad_i64_i32 v[8:9], s[40:41], s27, v1, v[70:71]
	v_mad_i64_i32 v[10:11], s[40:41], s42, v1, v[70:71]
	v_mad_i64_i32 v[12:13], s[40:41], s39, v1, v[70:71]
	v_cvt_pk_bf16_f32 v2, v2, v3
	v_cvt_pk_bf16_f32 v3, v4, v5
	global_store_short v[6:7], v2, off
	global_store_short_d16_hi v[8:9], v2, off
	global_store_short v[10:11], v3, off
	global_store_short_d16_hi v[12:13], v3, off
	s_add_i32 s33, s17, 4
	s_add_i32 s27, s17, 5
	s_add_i32 s42, s17, 6
	s_add_i32 s39, s17, 7
	v_pk_mul_f32 v[2:3], v[68:69], v[18:19]
	v_pk_mul_f32 v[4:5], v[68:69], v[20:21]
	v_mad_i64_i32 v[6:7], s[40:41], s33, v1, v[70:71]
	v_mad_i64_i32 v[8:9], s[40:41], s27, v1, v[70:71]
	v_mad_i64_i32 v[10:11], s[40:41], s42, v1, v[70:71]
	v_mad_i64_i32 v[12:13], s[40:41], s39, v1, v[70:71]
	v_cvt_pk_bf16_f32 v2, v2, v3
	v_cvt_pk_bf16_f32 v3, v4, v5
	global_store_short v[6:7], v2, off
	global_store_short_d16_hi v[8:9], v2, off
	global_store_short v[10:11], v3, off
	global_store_short_d16_hi v[12:13], v3, off
	s_add_i32 s33, s17, 8
	s_add_i32 s27, s17, 9
	s_add_i32 s42, s17, 10
	s_add_i32 s39, s17, 11
	v_pk_mul_f32 v[2:3], v[68:69], v[22:23]
	v_pk_mul_f32 v[4:5], v[68:69], v[24:25]
	v_mad_i64_i32 v[6:7], s[40:41], s33, v1, v[70:71]
	v_mad_i64_i32 v[8:9], s[40:41], s27, v1, v[70:71]
	v_mad_i64_i32 v[10:11], s[40:41], s42, v1, v[70:71]
	v_mad_i64_i32 v[12:13], s[40:41], s39, v1, v[70:71]
	v_cvt_pk_bf16_f32 v2, v2, v3
	v_cvt_pk_bf16_f32 v3, v4, v5
	global_store_short v[6:7], v2, off
	global_store_short_d16_hi v[8:9], v2, off
	global_store_short v[10:11], v3, off
	global_store_short_d16_hi v[12:13], v3, off
	s_add_i32 s33, s17, 12
	s_add_i32 s27, s17, 13
	s_add_i32 s42, s17, 14
	s_add_i32 s39, s17, 15
	v_pk_mul_f32 v[2:3], v[68:69], v[26:27]
	v_pk_mul_f32 v[4:5], v[68:69], v[28:29]
	v_mad_i64_i32 v[6:7], s[40:41], s33, v1, v[70:71]
	v_mad_i64_i32 v[8:9], s[40:41], s27, v1, v[70:71]
	v_mad_i64_i32 v[10:11], s[40:41], s42, v1, v[70:71]
	v_mad_i64_i32 v[12:13], s[40:41], s39, v1, v[70:71]
	v_cvt_pk_bf16_f32 v2, v2, v3
	v_cvt_pk_bf16_f32 v3, v4, v5
	global_store_short v[6:7], v2, off
	global_store_short_d16_hi v[8:9], v2, off
	global_store_short v[10:11], v3, off
	global_store_short_d16_hi v[12:13], v3, off
	s_add_i32 s33, s17, 16
	s_add_i32 s27, s17, 17
	s_add_i32 s42, s17, 18
	s_add_i32 s39, s17, 19
	v_pk_mul_f32 v[2:3], v[68:69], v[30:31]
	v_pk_mul_f32 v[4:5], v[68:69], v[32:33]
	v_mad_i64_i32 v[6:7], s[40:41], s33, v1, v[70:71]
	v_mad_i64_i32 v[8:9], s[40:41], s27, v1, v[70:71]
	v_mad_i64_i32 v[10:11], s[40:41], s42, v1, v[70:71]
	v_mad_i64_i32 v[12:13], s[40:41], s39, v1, v[70:71]
	v_cvt_pk_bf16_f32 v2, v2, v3
	v_cvt_pk_bf16_f32 v3, v4, v5
	global_store_short v[6:7], v2, off
	global_store_short_d16_hi v[8:9], v2, off
	global_store_short v[10:11], v3, off
	global_store_short_d16_hi v[12:13], v3, off
	s_add_i32 s33, s17, 20
	s_add_i32 s27, s17, 21
	s_add_i32 s42, s17, 22
	s_add_i32 s39, s17, 23
	v_pk_mul_f32 v[2:3], v[68:69], v[34:35]
	v_pk_mul_f32 v[4:5], v[68:69], v[36:37]
	v_mad_i64_i32 v[6:7], s[40:41], s33, v1, v[70:71]
	v_mad_i64_i32 v[8:9], s[40:41], s27, v1, v[70:71]
	v_mad_i64_i32 v[10:11], s[40:41], s42, v1, v[70:71]
	v_mad_i64_i32 v[12:13], s[40:41], s39, v1, v[70:71]
	v_cvt_pk_bf16_f32 v2, v2, v3
	v_cvt_pk_bf16_f32 v3, v4, v5
	global_store_short v[6:7], v2, off
	global_store_short_d16_hi v[8:9], v2, off
	global_store_short v[10:11], v3, off
	global_store_short_d16_hi v[12:13], v3, off
	s_add_i32 s33, s17, 24
	s_add_i32 s27, s17, 25
	s_add_i32 s42, s17, 26
	s_add_i32 s39, s17, 27
	v_pk_mul_f32 v[2:3], v[68:69], v[38:39]
	v_pk_mul_f32 v[4:5], v[68:69], v[40:41]
	v_mad_i64_i32 v[6:7], s[40:41], s33, v1, v[70:71]
	v_mad_i64_i32 v[8:9], s[40:41], s27, v1, v[70:71]
	v_mad_i64_i32 v[10:11], s[40:41], s42, v1, v[70:71]
	v_mad_i64_i32 v[12:13], s[40:41], s39, v1, v[70:71]
	v_cvt_pk_bf16_f32 v2, v2, v3
	v_cvt_pk_bf16_f32 v3, v4, v5
	global_store_short v[6:7], v2, off
	global_store_short_d16_hi v[8:9], v2, off
	global_store_short v[10:11], v3, off
	global_store_short_d16_hi v[12:13], v3, off
	s_add_i32 s33, s17, 28
	s_add_i32 s27, s17, 29
	s_add_i32 s42, s17, 30
	s_add_i32 s39, s17, 31
	v_pk_mul_f32 v[2:3], v[68:69], v[42:43]
	v_pk_mul_f32 v[4:5], v[68:69], v[44:45]
	v_mad_i64_i32 v[6:7], s[40:41], s33, v1, v[70:71]
	v_mad_i64_i32 v[8:9], s[40:41], s27, v1, v[70:71]
	v_mad_i64_i32 v[10:11], s[40:41], s42, v1, v[70:71]
	v_mad_i64_i32 v[12:13], s[40:41], s39, v1, v[70:71]
	v_cvt_pk_bf16_f32 v2, v2, v3
	v_cvt_pk_bf16_f32 v3, v4, v5
	global_store_short v[6:7], v2, off
	global_store_short_d16_hi v[8:9], v2, off
	global_store_short v[10:11], v3, off
	global_store_short_d16_hi v[12:13], v3, off
	s_branch .LBB0_179

.Lst_entry:
	v_add_u32_e32 v216, s68, v143
	v_add_u32_e32 v216, 0x100, v216
	v_ashrrev_i32_e32 v217, 31, v216
	v_lshlrev_b64 v[218:219], 12, v[216:217]
	v_lshlrev_b64 v[216:217], 6, v[216:217]
	v_lshl_add_u64 v[216:217], v[126:127], 0, v[216:217]
	v_lshl_add_u64 v[218:219], v[128:129], 0, v[218:219]
	v_lshl_add_u64 v[216:217], v[216:217], 0, s[64:65]
	v_cndmask_b32_e64 v216, v216, v218, s[14:15]
	v_subrev_u32_e32 v190, s30, v216
	v_mov_b32_e32 v216, 0x1000
	v_mov_b32_e32 v217, 0x40000
	v_cndmask_b32_e64 v197, v216, v217, s[14:15]
	v_add_u32_e32 v216, s68, v146
	v_add_u32_e32 v216, 0x100, v216
	v_ashrrev_i32_e32 v217, 31, v216
	v_lshlrev_b64 v[218:219], 12, v[216:217]
	v_lshlrev_b64 v[216:217], 6, v[216:217]
	v_lshl_add_u64 v[216:217], v[130:131], 0, v[216:217]
	v_lshl_add_u64 v[218:219], v[132:133], 0, v[218:219]
	v_lshl_add_u64 v[216:217], v[216:217], 0, s[64:65]
	v_cndmask_b32_e64 v216, v216, v218, s[16:17]
	v_subrev_u32_e32 v191, s30, v216
	v_mov_b32_e32 v216, 0x1000
	v_mov_b32_e32 v217, 0x40000
	v_cndmask_b32_e64 v208, v216, v217, s[16:17]
	v_add_u32_e32 v216, s68, v139
	v_add_u32_e32 v216, 0x100, v216
	v_ashrrev_i32_e32 v217, 31, v216
	v_lshlrev_b64 v[218:219], 12, v[216:217]
	v_lshlrev_b64 v[216:217], 6, v[216:217]
	v_lshl_add_u64 v[216:217], v[134:135], 0, v[216:217]
	v_lshl_add_u64 v[218:219], v[136:137], 0, v[218:219]
	v_lshl_add_u64 v[216:217], v[216:217], 0, s[64:65]
	v_cndmask_b32_e64 v216, v216, v218, s[18:19]
	v_subrev_u32_e32 v196, s30, v216
	v_mov_b32_e32 v216, 0x1000
	v_mov_b32_e32 v217, 0x40000
	v_cndmask_b32_e64 v209, v216, v217, s[18:19]
.Lst_top:
	s_add_i32 s93, s69, 0
	s_and_b32 s92, s93, 1
	s_cmp_gt_i32 s93, s50
	s_cbranch_scc1 .Lst_noqk0
	s_mul_i32 s4, s92, 0x5400
	s_add_i32 s24, s4, 0
	v_add3_u32 v153, s24, v192, v142
	ds_read_b128 v[220:223], v153
	ds_read_b128 v[224:227], v153 offset:32
	ds_read_b128 v[228:231], v153 offset:64
	ds_read_b128 v[232:235], v153 offset:96
	ds_read_b128 v[236:239], v153 offset:256
	ds_read_b128 v[240:243], v153 offset:288
	ds_read_b128 v[244:247], v153 offset:10752
	ds_read_b128 v[248:251], v153 offset:10784
	ds_read_b128 v[154:157], v153 offset:10816
	ds_read_b128 v[158:161], v153 offset:10848
	ds_read_b128 v[204:207], v153 offset:11008
	ds_read_b128 v[186:189], v153 offset:11040
	s_waitcnt lgkmcnt(11)
	v_mfma_f32_32x32x16_bf16 v[48:63], v[220:223], v[64:67], 0
	s_waitcnt lgkmcnt(10)
	v_mfma_f32_32x32x16_bf16 v[48:63], v[224:227], v[68:71], v[48:63]
	s_waitcnt lgkmcnt(9)
	v_mfma_f32_32x32x16_bf16 v[48:63], v[228:231], v[72:75], v[48:63]
	s_waitcnt lgkmcnt(8)
	v_mfma_f32_32x32x16_bf16 v[48:63], v[232:235], v[76:79], v[48:63]
	s_waitcnt lgkmcnt(7)
	v_mfma_f32_32x32x16_bf16 v[48:63], v[236:239], v[80:83], v[48:63]
	s_waitcnt lgkmcnt(6)
	v_mfma_f32_32x32x16_bf16 v[48:63], v[240:243], v[84:87], v[48:63]
	s_waitcnt lgkmcnt(5)
	v_mfma_f32_32x32x16_bf16 v[32:47], v[244:247], v[64:67], 0
	s_waitcnt lgkmcnt(4)
	v_mfma_f32_32x32x16_bf16 v[32:47], v[248:251], v[68:71], v[32:47]
	s_waitcnt lgkmcnt(3)
	v_mfma_f32_32x32x16_bf16 v[32:47], v[154:157], v[72:75], v[32:47]
	s_waitcnt lgkmcnt(2)
	v_mfma_f32_32x32x16_bf16 v[32:47], v[158:161], v[76:79], v[32:47]
	s_waitcnt lgkmcnt(1)
	v_mfma_f32_32x32x16_bf16 v[32:47], v[204:207], v[80:83], v[32:47]
	s_waitcnt lgkmcnt(0)
	v_mfma_f32_32x32x16_bf16 v[32:47], v[186:189], v[84:87], v[32:47]
	v_max_f32_e32 v162, v48, v48
	v_max_f32_e32 v153, v49, v49
	v_max_f32_e32 v153, v162, v153
	v_max3_f32 v153, v153, v50, v51
	v_max3_f32 v153, v153, v52, v53
	v_max3_f32 v153, v153, v54, v55
	v_max3_f32 v153, v153, v56, v57
	v_max3_f32 v153, v153, v58, v59
	v_max3_f32 v153, v153, v60, v61
	v_max3_f32 v153, v153, v62, v63
	s_nop 1
	v_max3_f32 v153, v153, v32, v33
	v_max3_f32 v153, v153, v34, v35
	v_max3_f32 v153, v153, v36, v37
	v_max3_f32 v153, v153, v38, v39
	v_max3_f32 v153, v153, v40, v41
	v_max3_f32 v153, v153, v42, v43
	v_max3_f32 v153, v153, v44, v45
	v_max3_f32 v153, v153, v46, v47
	v_mov_b32_e32 v154, v153
	s_nop 1
	v_permlane32_swap_b32_e32 v153, v154
	v_max_f32_e32 v154, v154, v154
	v_max_f32_e32 v153, v153, v153
	v_max_f32_e32 v153, v153, v154
.Lst_noqk0:
	s_cmp_gt_i32 s93, s50
	s_cbranch_scc1 .Lst_nosm0
	v_cmp_gt_f32_e32 vcc, v153, v152
	s_cbranch_vccz .Lst_norescale_0
	v_max_f32_e32 v153, v153, v153
	v_max_f32_e32 v154, v152, v152
	v_max_f32_e32 v153, v154, v153
	v_sub_f32_e32 v152, v152, v153
	v_exp_f32_e32 v152, v152
	s_nop 0
	v_pk_mul_f32 v[30:31], v[30:31], v[152:153] op_sel_hi:[1,0]
	v_pk_mul_f32 v[28:29], v[28:29], v[152:153] op_sel_hi:[1,0]
	v_pk_mul_f32 v[26:27], v[26:27], v[152:153] op_sel_hi:[1,0]
	v_pk_mul_f32 v[24:25], v[24:25], v[152:153] op_sel_hi:[1,0]
	v_pk_mul_f32 v[22:23], v[22:23], v[152:153] op_sel_hi:[1,0]
	v_pk_mul_f32 v[20:21], v[20:21], v[152:153] op_sel_hi:[1,0]
	v_pk_mul_f32 v[18:19], v[18:19], v[152:153] op_sel_hi:[1,0]
	v_pk_mul_f32 v[16:17], v[16:17], v[152:153] op_sel_hi:[1,0]
	v_pk_mul_f32 v[14:15], v[14:15], v[152:153] op_sel_hi:[1,0]
	v_pk_mul_f32 v[12:13], v[12:13], v[152:153] op_sel_hi:[1,0]
	v_pk_mul_f32 v[10:11], v[10:11], v[152:153] op_sel_hi:[1,0]
	v_pk_mul_f32 v[8:9], v[8:9], v[152:153] op_sel_hi:[1,0]
	v_pk_mul_f32 v[6:7], v[6:7], v[152:153] op_sel_hi:[1,0]
	v_pk_mul_f32 v[4:5], v[4:5], v[152:153] op_sel_hi:[1,0]
	v_pk_mul_f32 v[2:3], v[2:3], v[152:153] op_sel_hi:[1,0]
	v_pk_mul_f32 v[0:1], v[0:1], v[152:153] op_sel_hi:[1,0]
	v_mul_f32_e32 v151, v151, v152
	v_mov_b32_e32 v152, v153

.Lst_nosm0:
	s_cmp_ge_u32 s93, s51
	s_cbranch_scc1 .Lst_a0_nost
	s_xor_b32 s4, s92, 1
	s_mulk_i32 s4, 0x5400
	s_add_i32 s4, s4, 0
	s_waitcnt vmcnt(0)
	s_and_saveexec_b64 s[66:67], s[8:9]
	s_cbranch_execz .Lst_a0_s1
	v_add3_u32 v216, s4, v144, v145
	ds_write_b128 v216, v[100:103]
.Lst_a0_s1:
	s_or_b64 exec, exec, s[66:67]
	s_and_saveexec_b64 s[66:67], s[10:11]
	s_cbranch_execz .Lst_a0_s2
	v_add3_u32 v216, s4, v147, v148
	ds_write_b128 v216, v[104:107]
.Lst_a0_s2:
	s_or_b64 exec, exec, s[66:67]
	s_and_saveexec_b64 s[66:67], s[12:13]
	s_cbranch_execz .Lst_a0_s3
	v_add3_u32 v216, s4, v149, v150
	ds_write_b128 v216, v[108:111]

.Lst_a0_nost:
	s_cmp_ge_u32 s93, s60
	s_cbranch_scc1 .Lst_a0_nold
	global_load_dwordx4 v[100:103], v190, s[30:31]
	v_add_u32_e32 v190, v197, v190
	global_load_dwordx4 v[104:107], v191, s[30:31]
	v_add_u32_e32 v191, v208, v191
	s_and_saveexec_b64 s[66:67], s[12:13]
	s_cbranch_execz .Lst_a0_l2
	global_load_dwordx4 v[108:111], v196, s[30:31]
	v_add_u32_e32 v196, v209, v196

.Lst_a0_nold:
.Lst_bar2_0:
	s_waitcnt lgkmcnt(0)
	s_barrier
	s_add_i32 s93, s69, 1
	s_cmp_ge_u32 s93, s47
	s_cbranch_scc1 .Lst_exit
	s_and_b32 s92, s93, 1
	s_cmp_gt_i32 s93, s50
	s_cbranch_scc1 .Lst_noqk1
	s_mul_i32 s4, s92, 0x5400
	s_add_i32 s24, s4, 0
	v_add3_u32 v153, s24, v192, v142
	ds_read_b128 v[220:223], v153
	ds_read_b128 v[224:227], v153 offset:32
	ds_read_b128 v[228:231], v153 offset:64
	ds_read_b128 v[232:235], v153 offset:96
	ds_read_b128 v[236:239], v153 offset:256
	ds_read_b128 v[240:243], v153 offset:288
	ds_read_b128 v[244:247], v153 offset:10752
	ds_read_b128 v[248:251], v153 offset:10784
	ds_read_b128 v[154:157], v153 offset:10816
	ds_read_b128 v[158:161], v153 offset:10848
	ds_read_b128 v[204:207], v153 offset:11008
	ds_read_b128 v[186:189], v153 offset:11040
	s_waitcnt lgkmcnt(11)
	v_mfma_f32_32x32x16_bf16 v[48:63], v[220:223], v[64:67], 0
	s_waitcnt lgkmcnt(10)
	v_mfma_f32_32x32x16_bf16 v[48:63], v[224:227], v[68:71], v[48:63]
	s_waitcnt lgkmcnt(9)
	v_mfma_f32_32x32x16_bf16 v[48:63], v[228:231], v[72:75], v[48:63]
	s_waitcnt lgkmcnt(8)
	v_mfma_f32_32x32x16_bf16 v[48:63], v[232:235], v[76:79], v[48:63]
	s_waitcnt lgkmcnt(7)
	v_mfma_f32_32x32x16_bf16 v[48:63], v[236:239], v[80:83], v[48:63]
	s_waitcnt lgkmcnt(6)
	v_mfma_f32_32x32x16_bf16 v[48:63], v[240:243], v[84:87], v[48:63]
	s_waitcnt lgkmcnt(5)
	v_mfma_f32_32x32x16_bf16 v[32:47], v[244:247], v[64:67], 0
	s_waitcnt lgkmcnt(4)
	v_mfma_f32_32x32x16_bf16 v[32:47], v[248:251], v[68:71], v[32:47]
	s_waitcnt lgkmcnt(3)
	v_mfma_f32_32x32x16_bf16 v[32:47], v[154:157], v[72:75], v[32:47]
	s_waitcnt lgkmcnt(2)
	v_mfma_f32_32x32x16_bf16 v[32:47], v[158:161], v[76:79], v[32:47]
	s_waitcnt lgkmcnt(1)
	v_mfma_f32_32x32x16_bf16 v[32:47], v[204:207], v[80:83], v[32:47]
	s_waitcnt lgkmcnt(0)
	v_mfma_f32_32x32x16_bf16 v[32:47], v[186:189], v[84:87], v[32:47]
	v_max_f32_e32 v162, v48, v48
	v_max_f32_e32 v153, v49, v49
	v_max_f32_e32 v153, v162, v153
	v_max3_f32 v153, v153, v50, v51
	v_max3_f32 v153, v153, v52, v53
	v_max3_f32 v153, v153, v54, v55
	v_max3_f32 v153, v153, v56, v57
	v_max3_f32 v153, v153, v58, v59
	v_max3_f32 v153, v153, v60, v61
	v_max3_f32 v153, v153, v62, v63
	s_nop 1
	v_max3_f32 v153, v153, v32, v33
	v_max3_f32 v153, v153, v34, v35
	v_max3_f32 v153, v153, v36, v37
	v_max3_f32 v153, v153, v38, v39
	v_max3_f32 v153, v153, v40, v41
	v_max3_f32 v153, v153, v42, v43
	v_max3_f32 v153, v153, v44, v45
	v_max3_f32 v153, v153, v46, v47
	v_mov_b32_e32 v154, v153
	s_nop 1
	v_permlane32_swap_b32_e32 v153, v154
	v_max_f32_e32 v154, v154, v154
	v_max_f32_e32 v153, v153, v153
	v_max_f32_e32 v153, v153, v154

.Lst_nosm1:
	s_cmp_ge_u32 s93, s51
	s_cbranch_scc1 .Lst_a1_nost
	s_xor_b32 s4, s92, 1
	s_mulk_i32 s4, 0x5400
	s_add_i32 s4, s4, 0
	s_waitcnt vmcnt(0)
	s_and_saveexec_b64 s[66:67], s[8:9]
	s_cbranch_execz .Lst_a1_s1
	v_add3_u32 v216, s4, v144, v145
	ds_write_b128 v216, v[112:115]
.Lst_a1_s1:
	s_or_b64 exec, exec, s[66:67]
	s_and_saveexec_b64 s[66:67], s[10:11]
	s_cbranch_execz .Lst_a1_s2
	v_add3_u32 v216, s4, v147, v148
	ds_write_b128 v216, v[116:119]
.Lst_a1_s2:
	s_or_b64 exec, exec, s[66:67]
	s_and_saveexec_b64 s[66:67], s[12:13]
	s_cbranch_execz .Lst_a1_s3
	v_add3_u32 v216, s4, v149, v150
	ds_write_b128 v216, v[120:123]

.Lst_a1_nost:
	s_cmp_ge_u32 s93, s60
	s_cbranch_scc1 .Lst_a1_nold
	global_load_dwordx4 v[112:115], v190, s[30:31]
	v_add_u32_e32 v190, v197, v190
	global_load_dwordx4 v[116:119], v191, s[30:31]
	v_add_u32_e32 v191, v208, v191
	s_and_saveexec_b64 s[66:67], s[12:13]
	s_cbranch_execz .Lst_a1_l2
	global_load_dwordx4 v[120:123], v196, s[30:31]
	v_add_u32_e32 v196, v209, v196

.Lst_a1_nold:
.Lst_bar2_1:
	s_waitcnt lgkmcnt(0)
	s_barrier
	s_add_i32 s93, s69, 2
	s_cmp_ge_u32 s93, s47
	s_cbranch_scc1 .Lst_exit
	s_and_b32 s92, s93, 1
	s_cmp_gt_i32 s93, s50
	s_cbranch_scc1 .Lst_noqk2
	s_mul_i32 s4, s92, 0x5400
	s_add_i32 s24, s4, 0
	v_add3_u32 v153, s24, v192, v142
	ds_read_b128 v[220:223], v153
	ds_read_b128 v[224:227], v153 offset:32
	ds_read_b128 v[228:231], v153 offset:64
	ds_read_b128 v[232:235], v153 offset:96
	ds_read_b128 v[236:239], v153 offset:256
	ds_read_b128 v[240:243], v153 offset:288
	ds_read_b128 v[244:247], v153 offset:10752
	ds_read_b128 v[248:251], v153 offset:10784
	ds_read_b128 v[154:157], v153 offset:10816
	ds_read_b128 v[158:161], v153 offset:10848
	ds_read_b128 v[204:207], v153 offset:11008
	ds_read_b128 v[186:189], v153 offset:11040
	s_waitcnt lgkmcnt(11)
	v_mfma_f32_32x32x16_bf16 v[48:63], v[220:223], v[64:67], 0
	s_waitcnt lgkmcnt(10)
	v_mfma_f32_32x32x16_bf16 v[48:63], v[224:227], v[68:71], v[48:63]
	s_waitcnt lgkmcnt(9)
	v_mfma_f32_32x32x16_bf16 v[48:63], v[228:231], v[72:75], v[48:63]
	s_waitcnt lgkmcnt(8)
	v_mfma_f32_32x32x16_bf16 v[48:63], v[232:235], v[76:79], v[48:63]
	s_waitcnt lgkmcnt(7)
	v_mfma_f32_32x32x16_bf16 v[48:63], v[236:239], v[80:83], v[48:63]
	s_waitcnt lgkmcnt(6)
	v_mfma_f32_32x32x16_bf16 v[48:63], v[240:243], v[84:87], v[48:63]
	s_waitcnt lgkmcnt(5)
	v_mfma_f32_32x32x16_bf16 v[32:47], v[244:247], v[64:67], 0
	s_waitcnt lgkmcnt(4)
	v_mfma_f32_32x32x16_bf16 v[32:47], v[248:251], v[68:71], v[32:47]
	s_waitcnt lgkmcnt(3)
	v_mfma_f32_32x32x16_bf16 v[32:47], v[154:157], v[72:75], v[32:47]
	s_waitcnt lgkmcnt(2)
	v_mfma_f32_32x32x16_bf16 v[32:47], v[158:161], v[76:79], v[32:47]
	s_waitcnt lgkmcnt(1)
	v_mfma_f32_32x32x16_bf16 v[32:47], v[204:207], v[80:83], v[32:47]
	s_waitcnt lgkmcnt(0)
	v_mfma_f32_32x32x16_bf16 v[32:47], v[186:189], v[84:87], v[32:47]
	v_max_f32_e32 v162, v48, v48
	v_max_f32_e32 v153, v49, v49
	v_max_f32_e32 v153, v162, v153
	v_max3_f32 v153, v153, v50, v51
	v_max3_f32 v153, v153, v52, v53
	v_max3_f32 v153, v153, v54, v55
	v_max3_f32 v153, v153, v56, v57
	v_max3_f32 v153, v153, v58, v59
	v_max3_f32 v153, v153, v60, v61
	v_max3_f32 v153, v153, v62, v63
	s_nop 1
	v_max3_f32 v153, v153, v32, v33
	v_max3_f32 v153, v153, v34, v35
	v_max3_f32 v153, v153, v36, v37
	v_max3_f32 v153, v153, v38, v39
	v_max3_f32 v153, v153, v40, v41
	v_max3_f32 v153, v153, v42, v43
	v_max3_f32 v153, v153, v44, v45
	v_max3_f32 v153, v153, v46, v47
	v_mov_b32_e32 v154, v153
	s_nop 1
	v_permlane32_swap_b32_e32 v153, v154
	v_max_f32_e32 v154, v154, v154
	v_max_f32_e32 v153, v153, v153
	v_max_f32_e32 v153, v153, v154

.Lst_nosm2:
	s_cmp_ge_u32 s93, s51
	s_cbranch_scc1 .Lst_a2_nost
	s_xor_b32 s4, s92, 1
	s_mulk_i32 s4, 0x5400
	s_add_i32 s4, s4, 0
	s_waitcnt vmcnt(0)
	s_and_saveexec_b64 s[66:67], s[8:9]
	s_cbranch_execz .Lst_a2_s1
	v_add3_u32 v216, s4, v144, v145
	ds_write_b128 v216, v[88:91]
.Lst_a2_s1:
	s_or_b64 exec, exec, s[66:67]
	s_and_saveexec_b64 s[66:67], s[10:11]
	s_cbranch_execz .Lst_a2_s2
	v_add3_u32 v216, s4, v147, v148
	ds_write_b128 v216, v[92:95]
.Lst_a2_s2:
	s_or_b64 exec, exec, s[66:67]
	s_and_saveexec_b64 s[66:67], s[12:13]
	s_cbranch_execz .Lst_a2_s3
	v_add3_u32 v216, s4, v149, v150
	ds_write_b128 v216, v[96:99]

.Lst_a2_nost:
	s_cmp_ge_u32 s93, s60
	s_cbranch_scc1 .Lst_a2_nold
	global_load_dwordx4 v[88:91], v190, s[30:31]
	v_add_u32_e32 v190, v197, v190
	global_load_dwordx4 v[92:95], v191, s[30:31]
	v_add_u32_e32 v191, v208, v191
	s_and_saveexec_b64 s[66:67], s[12:13]
	s_cbranch_execz .Lst_a2_l2
	global_load_dwordx4 v[96:99], v196, s[30:31]
	v_add_u32_e32 v196, v209, v196

.Lst_a2_nold:
.Lst_bar2_2:
	s_waitcnt lgkmcnt(0)
	s_barrier
	s_add_i32 s69, s69, 3
	s_addk_i32 s68, 0xc0
	s_cmp_lt_u32 s69, s47
	s_cbranch_scc1 .Lst_top
.Lst_exit:
.Lst_done:
.LBB0_1016:
	v_and_b32_e32 v33, 64, v211
	v_xor_b32_e32 v32, 32, v211
	v_add_u32_e32 v33, 64, v33
	v_cmp_lt_i32_e32 vcc, v32, v33
	s_lshl_b32 s60, s46, 7
	v_lshlrev_b32_e32 v192, 1, v138
	v_cndmask_b32_e32 v32, v211, v32, vcc
	v_lshlrev_b32_e32 v32, 2, v32
	ds_bpermute_b32 v34, v32, v151
	v_lshlrev_b64 v[32:33], 11, v[124:125]
	v_lshl_add_u64 v[32:33], s[48:49], 0, v[32:33]
	v_lshl_add_u64 v[32:33], v[32:33], 0, s[60:61]
	v_lshl_add_u64 v[32:33], v[32:33], 0, v[192:193]
	s_waitcnt lgkmcnt(0)
	v_add_f32_e32 v34, v151, v34
	v_div_scale_f32 v35, s[4:5], v34, v34, 1.0
	v_rcp_f32_e32 v36, v35
	s_mov_b64 s[8:9], 0
	v_fma_f32 v37, -v35, v36, 1.0
	v_fmac_f32_e32 v36, v37, v36
	v_div_scale_f32 v37, vcc, 1.0, v34, 1.0
	v_mul_f32_e32 v38, v37, v36
	v_fma_f32 v39, -v35, v38, v37
	v_fmac_f32_e32 v38, v39, v36
	v_fma_f32 v35, -v35, v38, v37
	v_div_fmas_f32 v35, v35, v36, v38
	v_div_fixup_f32 v34, v35, v34, 1.0
	v_pk_mul_f32 v[16:17], v[16:17], v[34:35] op_sel_hi:[1,0]
	v_pk_mul_f32 v[18:19], v[18:19], v[34:35] op_sel_hi:[1,0]
	v_pk_mul_f32 v[0:1], v[0:1], v[34:35] op_sel_hi:[1,0]
	v_pk_mul_f32 v[2:3], v[2:3], v[34:35] op_sel_hi:[1,0]
	v_cvt_pk_bf16_f32 v16, v16, v17
	v_cvt_pk_bf16_f32 v17, v18, v19
	v_pk_mul_f32 v[18:19], v[20:21], v[34:35] op_sel_hi:[1,0]
	v_pk_mul_f32 v[20:21], v[22:23], v[34:35] op_sel_hi:[1,0]
	v_cvt_pk_bf16_f32 v0, v0, v1
	v_cvt_pk_bf16_f32 v1, v2, v3
	v_pk_mul_f32 v[2:3], v[4:5], v[34:35] op_sel_hi:[1,0]
	v_pk_mul_f32 v[4:5], v[6:7], v[34:35] op_sel_hi:[1,0]
	v_cvt_pk_bf16_f32 v18, v18, v19
	v_cvt_pk_bf16_f32 v19, v20, v21
	v_cvt_pk_bf16_f32 v2, v2, v3
	v_cvt_pk_bf16_f32 v3, v4, v5
	v_permlane32_swap_b32_e32 v16, v18
	v_permlane32_swap_b32_e32 v17, v19
	v_permlane32_swap_b32_e32 v0, v2
	v_permlane32_swap_b32_e32 v1, v3
	global_store_dwordx4 v[32:33], v[16:19], off
	global_store_dwordx4 v[32:33], v[0:3], off offset:64
	v_pk_mul_f32 v[20:21], v[30:31], v[34:35] op_sel_hi:[1,0]
	v_pk_mul_f32 v[16:17], v[24:25], v[34:35] op_sel_hi:[1,0]
	v_pk_mul_f32 v[18:19], v[26:27], v[34:35] op_sel_hi:[1,0]
	v_pk_mul_f32 v[0:1], v[8:9], v[34:35] op_sel_hi:[1,0]
	v_pk_mul_f32 v[2:3], v[10:11], v[34:35] op_sel_hi:[1,0]
	v_cvt_pk_bf16_f32 v16, v16, v17
	v_cvt_pk_bf16_f32 v17, v18, v19
	v_pk_mul_f32 v[18:19], v[28:29], v[34:35] op_sel_hi:[1,0]
	v_cvt_pk_bf16_f32 v0, v0, v1
	v_cvt_pk_bf16_f32 v1, v2, v3
	v_pk_mul_f32 v[2:3], v[12:13], v[34:35] op_sel_hi:[1,0]
	v_pk_mul_f32 v[4:5], v[14:15], v[34:35] op_sel_hi:[1,0]
	v_cvt_pk_bf16_f32 v18, v18, v19
	v_cvt_pk_bf16_f32 v19, v20, v21
	v_cvt_pk_bf16_f32 v2, v2, v3
	v_cvt_pk_bf16_f32 v3, v4, v5
	v_permlane32_swap_b32_e32 v16, v18
	v_permlane32_swap_b32_e32 v17, v19
	v_permlane32_swap_b32_e32 v0, v2
	v_permlane32_swap_b32_e32 v1, v3
	global_store_dwordx4 v[32:33], v[16:19], off offset:32
	global_store_dwordx4 v[32:33], v[0:3], off offset:96
